# FFN-in K-loop: leading wave half retires its counted LDS-DMA wait one slot later
# baseline (speedup 1.0000x reference)
.LBB0_663:
	s_ashr_i32 s61, s60, 31
	s_lshl_b64 s[10:11], s[60:61], 19
	s_add_u32 s62, s21, s10
	s_addc_u32 s63, s24, s11
	s_and_b64 s[10:11], s[12:13], exec
	s_cselect_b32 s10, s63, s69
	s_cselect_b32 s11, s62, s68
	s_ashr_i32 s59, s58, 31
	s_lshl_b64 s[64:65], s[58:59], 19
	s_add_u32 s64, s27, s64
	s_addc_u32 s65, s34, s65
	s_and_b64 s[72:73], s[12:13], exec
	s_cselect_b32 s15, s65, s71
	s_cselect_b32 s59, s64, s70
	s_add_u32 s68, s68, 0x40080
	s_addc_u32 s69, s69, 0
	s_add_u32 s61, s70, 0x100
	s_addc_u32 s67, s71, 0
	s_mov_b32 s80, -2
	s_add_u32 s6, s68, 0xfffc0080
	s_addc_u32 s33, s69, -1
	s_add_i32 s82, 0, 0x10000
	s_cmp_eq_u32 s80, 12
	s_cselect_b32 s73, s10, s33
	s_cselect_b32 s72, s11, s6
	v_add_u32_e32 v2, s82, v148
	s_cselect_b32 s71, s15, s67
	s_cselect_b32 s70, s59, s61
	s_add_i32 s6, 0, 0x14000
	ds_read_b128 v[152:155], v2
	ds_read_b128 v[156:159], v2 offset:1024
	ds_read_b128 v[160:163], v2 offset:2048
	ds_read_b128 v[168:171], v2 offset:3072
	v_add_u32_e32 v2, s6, v148
	ds_read_b128 v[174:177], v2
	ds_read_b128 v[178:181], v2 offset:1024
	ds_read_b128 v[182:185], v2 offset:2048
	ds_read_b128 v[186:189], v2 offset:3072
	v_lshl_add_u64 v[146:147], s[68:69], 0, v[142:143]
	s_add_i32 m0, s35, 0xc000
	ds_read_b128 v[200:203], v151
	ds_read_b128 v[204:207], v151 offset:1024
	ds_read_b128 v[208:211], v151 offset:2048
	ds_read_b128 v[212:215], v151 offset:3072
	ds_read_b128 v[216:219], v151 offset:4096
	ds_read_b128 v[220:223], v151 offset:5120
	ds_read_b128 v[224:227], v151 offset:6144
	ds_read_b128 v[228:231], v151 offset:7168
	global_load_lds_dwordx4 v[146:147], off
	v_lshl_add_u64 v[146:147], s[68:69], 0, v[144:145]
	s_add_i32 m0, s35, 0xe000
	s_nop 0
	global_load_lds_dwordx4 v[146:147], off
	s_and_b64 vcc, exec, s[18:19]
	s_cbranch_vccnz .Llw4_0a
	s_waitcnt vmcnt(8)
.Llw4_0a:
	s_waitcnt lgkmcnt(0)
	s_barrier
	s_waitcnt lgkmcnt(0)
	v_mfma_f32_16x16x32_bf16 v[128:131], v[152:155], v[200:203], 0
	v_mfma_f32_16x16x32_bf16 v[120:123], v[160:163], v[200:203], 0
	v_mfma_f32_16x16x32_bf16 v[112:115], v[152:155], v[208:211], 0
	v_mfma_f32_16x16x32_bf16 v[104:107], v[160:163], v[208:211], 0
	v_mfma_f32_16x16x32_bf16 v[96:99], v[152:155], v[216:219], 0
	v_mfma_f32_16x16x32_bf16 v[88:91], v[160:163], v[216:219], 0
	v_mfma_f32_16x16x32_bf16 v[80:83], v[152:155], v[224:227], 0
	v_mfma_f32_16x16x32_bf16 v[72:75], v[160:163], v[224:227], 0
	v_mfma_f32_16x16x32_bf16 v[128:131], v[156:159], v[204:207], v[128:131]
	v_mfma_f32_16x16x32_bf16 v[120:123], v[168:171], v[204:207], v[120:123]
	v_mfma_f32_16x16x32_bf16 v[112:115], v[156:159], v[212:215], v[112:115]
	v_mfma_f32_16x16x32_bf16 v[104:107], v[168:171], v[212:215], v[104:107]
	v_mfma_f32_16x16x32_bf16 v[96:99], v[156:159], v[220:223], v[96:99]
	v_mfma_f32_16x16x32_bf16 v[88:91], v[168:171], v[220:223], v[88:91]
	v_mfma_f32_16x16x32_bf16 v[80:83], v[156:159], v[228:231], v[80:83]
	v_mfma_f32_16x16x32_bf16 v[72:75], v[168:171], v[228:231], v[72:75]
	v_mfma_f32_16x16x32_bf16 v[124:127], v[174:177], v[200:203], 0
	v_mfma_f32_16x16x32_bf16 v[116:119], v[182:185], v[200:203], 0
	v_mfma_f32_16x16x32_bf16 v[108:111], v[174:177], v[208:211], 0
	v_mfma_f32_16x16x32_bf16 v[100:103], v[182:185], v[208:211], 0
	v_mfma_f32_16x16x32_bf16 v[92:95], v[174:177], v[216:219], 0
	v_mfma_f32_16x16x32_bf16 v[84:87], v[182:185], v[216:219], 0
	v_mfma_f32_16x16x32_bf16 v[76:79], v[174:177], v[224:227], 0
	v_mfma_f32_16x16x32_bf16 v[68:71], v[182:185], v[224:227], 0
	v_mfma_f32_16x16x32_bf16 v[124:127], v[178:181], v[204:207], v[124:127]
	v_mfma_f32_16x16x32_bf16 v[116:119], v[186:189], v[204:207], v[116:119]
	v_mfma_f32_16x16x32_bf16 v[108:111], v[178:181], v[212:215], v[108:111]
	v_mfma_f32_16x16x32_bf16 v[100:103], v[186:189], v[212:215], v[100:103]
	v_mfma_f32_16x16x32_bf16 v[92:95], v[178:181], v[220:223], v[92:95]
	v_mfma_f32_16x16x32_bf16 v[84:87], v[186:189], v[220:223], v[84:87]
	v_mfma_f32_16x16x32_bf16 v[76:79], v[178:181], v[228:231], v[76:79]
	v_mfma_f32_16x16x32_bf16 v[68:71], v[186:189], v[228:231], v[68:71]
	s_cbranch_vccz .Llw4_0b
	s_waitcnt vmcnt(8)
.Llw4_0b:
	s_barrier
	s_add_i32 s33, s82, s20
	v_lshl_add_u64 v[146:147], s[70:71], 0, v[134:135]
	s_mov_b32 m0, s33
	ds_read_b128 v[200:203], v151 offset:16384
	ds_read_b128 v[204:207], v151 offset:17408
	ds_read_b128 v[208:211], v151 offset:18432
	ds_read_b128 v[212:215], v151 offset:19456
	ds_read_b128 v[216:219], v151 offset:20480
	ds_read_b128 v[220:223], v151 offset:21504
	ds_read_b128 v[224:227], v151 offset:22528
	ds_read_b128 v[228:231], v151 offset:23552
	global_load_lds_dwordx4 v[146:147], off
	s_add_i32 m0, s33, 0x2000
	s_add_u32 s82, s70, 0x40000
	v_lshl_add_u64 v[164:165], s[70:71], 0, v[138:139]
	s_addc_u32 s83, s71, 0
	s_add_i32 s6, s6, s20
	global_load_lds_dwordx4 v[164:165], off
	v_lshl_add_u64 v[232:233], s[82:83], 0, v[134:135]
	s_mov_b32 m0, s6
	v_lshl_add_u64 v[234:235], s[72:73], 0, v[136:137]
	global_load_lds_dwordx4 v[232:233], off
	v_lshl_add_u64 v[232:233], s[82:83], 0, v[138:139]
	s_add_i32 m0, s6, 0x2000
	s_nop 0
	global_load_lds_dwordx4 v[232:233], off
	v_lshl_add_u64 v[232:233], s[72:73], 0, v[132:133]
	s_mov_b32 m0, s35
	s_nop 0
	global_load_lds_dwordx4 v[232:233], off
	s_mov_b32 m0, s54
	s_nop 0
	global_load_lds_dwordx4 v[234:235], off
	s_and_b64 vcc, exec, s[18:19]
	s_cbranch_vccnz .Llw4_1a
	s_waitcnt vmcnt(8)
.Llw4_1a:
	s_waitcnt lgkmcnt(0)
	s_barrier
	s_waitcnt lgkmcnt(0)
	v_mfma_f32_16x16x32_bf16 v[64:67], v[152:155], v[200:203], 0
	v_mfma_f32_16x16x32_bf16 v[56:59], v[160:163], v[200:203], 0
	v_mfma_f32_16x16x32_bf16 v[48:51], v[152:155], v[208:211], 0
	v_mfma_f32_16x16x32_bf16 v[40:43], v[160:163], v[208:211], 0
	v_mfma_f32_16x16x32_bf16 v[32:35], v[152:155], v[216:219], 0
	v_mfma_f32_16x16x32_bf16 v[24:27], v[160:163], v[216:219], 0
	v_mfma_f32_16x16x32_bf16 v[16:19], v[152:155], v[224:227], 0
	v_mfma_f32_16x16x32_bf16 v[8:11], v[160:163], v[224:227], 0
	v_mfma_f32_16x16x32_bf16 v[64:67], v[156:159], v[204:207], v[64:67]
	v_mfma_f32_16x16x32_bf16 v[56:59], v[168:171], v[204:207], v[56:59]
	v_mfma_f32_16x16x32_bf16 v[48:51], v[156:159], v[212:215], v[48:51]
	v_mfma_f32_16x16x32_bf16 v[40:43], v[168:171], v[212:215], v[40:43]
	v_mfma_f32_16x16x32_bf16 v[32:35], v[156:159], v[220:223], v[32:35]
	v_mfma_f32_16x16x32_bf16 v[24:27], v[168:171], v[220:223], v[24:27]
	v_mfma_f32_16x16x32_bf16 v[16:19], v[156:159], v[228:231], v[16:19]
	v_mfma_f32_16x16x32_bf16 v[8:11], v[168:171], v[228:231], v[8:11]
	v_mfma_f32_16x16x32_bf16 v[60:63], v[174:177], v[200:203], 0
	v_mfma_f32_16x16x32_bf16 v[52:55], v[182:185], v[200:203], 0
	v_mfma_f32_16x16x32_bf16 v[44:47], v[174:177], v[208:211], 0
	v_mfma_f32_16x16x32_bf16 v[36:39], v[182:185], v[208:211], 0
	v_mfma_f32_16x16x32_bf16 v[28:31], v[174:177], v[216:219], 0
	v_mfma_f32_16x16x32_bf16 v[20:23], v[182:185], v[216:219], 0
	v_mfma_f32_16x16x32_bf16 v[12:15], v[174:177], v[224:227], 0
	v_mfma_f32_16x16x32_bf16 v[4:7], v[182:185], v[224:227], 0
	v_mfma_f32_16x16x32_bf16 v[60:63], v[178:181], v[204:207], v[60:63]
	v_mfma_f32_16x16x32_bf16 v[52:55], v[186:189], v[204:207], v[52:55]
	v_mfma_f32_16x16x32_bf16 v[44:47], v[178:181], v[212:215], v[44:47]
	v_mfma_f32_16x16x32_bf16 v[36:39], v[186:189], v[212:215], v[36:39]
	v_mfma_f32_16x16x32_bf16 v[28:31], v[178:181], v[220:223], v[28:31]
	v_mfma_f32_16x16x32_bf16 v[20:23], v[186:189], v[220:223], v[20:23]
	v_mfma_f32_16x16x32_bf16 v[12:15], v[178:181], v[228:231], v[12:15]
	v_mfma_f32_16x16x32_bf16 v[4:7], v[186:189], v[228:231], v[4:7]
	s_cbranch_vccz .Llw4_1b
	s_waitcnt vmcnt(8)
.Llw4_1b:
	s_barrier
	s_add_i32 s6, 0, 0x18000
	v_add_u32_e32 v2, s6, v148
	s_add_i32 s33, 0, 0x1c000
	ds_read_b128 v[152:155], v2
	ds_read_b128 v[156:159], v2 offset:1024
	ds_read_b128 v[160:163], v2 offset:2048
	ds_read_b128 v[168:171], v2 offset:3072
	v_add_u32_e32 v2, s33, v148
	ds_read_b128 v[174:177], v2
	ds_read_b128 v[178:181], v2 offset:1024
	ds_read_b128 v[182:185], v2 offset:2048
	ds_read_b128 v[186:189], v2 offset:3072
	s_add_u32 s72, s72, 0x40000
	s_addc_u32 s73, s73, 0
	s_mov_b32 m0, s55
	v_lshl_add_u64 v[236:237], s[72:73], 0, v[132:133]
	ds_read_b128 v[200:203], v151 offset:32768
	ds_read_b128 v[204:207], v151 offset:33792
	ds_read_b128 v[208:211], v151 offset:34816
	ds_read_b128 v[212:215], v151 offset:35840
	ds_read_b128 v[216:219], v151 offset:36864
	ds_read_b128 v[220:223], v151 offset:37888
	ds_read_b128 v[224:227], v151 offset:38912
	ds_read_b128 v[228:231], v151 offset:39936
	global_load_lds_dwordx4 v[236:237], off
	v_lshl_add_u64 v[236:237], s[72:73], 0, v[136:137]
	s_mov_b32 m0, s56
	s_nop 0
	global_load_lds_dwordx4 v[236:237], off
	s_and_b64 vcc, exec, s[18:19]
	s_cbranch_vccnz .Llw4_2a
	s_waitcnt vmcnt(8)
.Llw4_2a:
	s_waitcnt lgkmcnt(0)
	s_barrier
	s_waitcnt lgkmcnt(0)
	v_mfma_f32_16x16x32_bf16 v[128:131], v[152:155], v[200:203], v[128:131]
	v_mfma_f32_16x16x32_bf16 v[120:123], v[160:163], v[200:203], v[120:123]
	v_mfma_f32_16x16x32_bf16 v[112:115], v[152:155], v[208:211], v[112:115]
	v_mfma_f32_16x16x32_bf16 v[104:107], v[160:163], v[208:211], v[104:107]
	v_mfma_f32_16x16x32_bf16 v[96:99], v[152:155], v[216:219], v[96:99]
	v_mfma_f32_16x16x32_bf16 v[88:91], v[160:163], v[216:219], v[88:91]
	v_mfma_f32_16x16x32_bf16 v[80:83], v[152:155], v[224:227], v[80:83]
	v_mfma_f32_16x16x32_bf16 v[72:75], v[160:163], v[224:227], v[72:75]
	v_mfma_f32_16x16x32_bf16 v[128:131], v[156:159], v[204:207], v[128:131]
	v_mfma_f32_16x16x32_bf16 v[120:123], v[168:171], v[204:207], v[120:123]
	v_mfma_f32_16x16x32_bf16 v[112:115], v[156:159], v[212:215], v[112:115]
	v_mfma_f32_16x16x32_bf16 v[104:107], v[168:171], v[212:215], v[104:107]
	v_mfma_f32_16x16x32_bf16 v[96:99], v[156:159], v[220:223], v[96:99]
	v_mfma_f32_16x16x32_bf16 v[88:91], v[168:171], v[220:223], v[88:91]
	v_mfma_f32_16x16x32_bf16 v[80:83], v[156:159], v[228:231], v[80:83]
	v_mfma_f32_16x16x32_bf16 v[72:75], v[168:171], v[228:231], v[72:75]
	v_mfma_f32_16x16x32_bf16 v[124:127], v[174:177], v[200:203], v[124:127]
	v_mfma_f32_16x16x32_bf16 v[116:119], v[182:185], v[200:203], v[116:119]
	v_mfma_f32_16x16x32_bf16 v[108:111], v[174:177], v[208:211], v[108:111]
	v_mfma_f32_16x16x32_bf16 v[100:103], v[182:185], v[208:211], v[100:103]
	v_mfma_f32_16x16x32_bf16 v[92:95], v[174:177], v[216:219], v[92:95]
	v_mfma_f32_16x16x32_bf16 v[84:87], v[182:185], v[216:219], v[84:87]
	v_mfma_f32_16x16x32_bf16 v[76:79], v[174:177], v[224:227], v[76:79]
	v_mfma_f32_16x16x32_bf16 v[68:71], v[182:185], v[224:227], v[68:71]
	v_mfma_f32_16x16x32_bf16 v[124:127], v[178:181], v[204:207], v[124:127]
	v_mfma_f32_16x16x32_bf16 v[116:119], v[186:189], v[204:207], v[116:119]
	v_mfma_f32_16x16x32_bf16 v[108:111], v[178:181], v[212:215], v[108:111]
	v_mfma_f32_16x16x32_bf16 v[100:103], v[186:189], v[212:215], v[100:103]
	v_mfma_f32_16x16x32_bf16 v[92:95], v[178:181], v[220:223], v[92:95]
	v_mfma_f32_16x16x32_bf16 v[84:87], v[186:189], v[220:223], v[84:87]
	v_mfma_f32_16x16x32_bf16 v[76:79], v[178:181], v[228:231], v[76:79]
	v_mfma_f32_16x16x32_bf16 v[68:71], v[186:189], v[228:231], v[68:71]
	s_cbranch_vccz .Llw4_2b
	s_waitcnt vmcnt(8)
.Llw4_2b:
	s_barrier
	s_add_i32 s6, s6, s20
	v_lshl_add_u64 v[146:147], v[146:147], 0, s[30:31]
	s_mov_b32 m0, s6
	ds_read_b128 v[200:203], v151 offset:49152
	ds_read_b128 v[204:207], v151 offset:50176
	ds_read_b128 v[208:211], v151 offset:51200
	ds_read_b128 v[212:215], v151 offset:52224
	ds_read_b128 v[216:219], v151 offset:53248
	ds_read_b128 v[220:223], v151 offset:54272
	ds_read_b128 v[224:227], v151 offset:55296
	ds_read_b128 v[228:231], v151 offset:56320
	global_load_lds_dwordx4 v[146:147], off
	s_add_i32 m0, s6, 0x2000
	s_add_u32 s70, s70, 0x40080
	v_lshl_add_u64 v[146:147], v[164:165], 0, s[30:31]
	s_addc_u32 s71, s71, 0
	s_add_i32 s6, s33, s20
	global_load_lds_dwordx4 v[146:147], off
	v_lshl_add_u64 v[146:147], s[70:71], 0, v[134:135]
	s_mov_b32 m0, s6
	s_nop 0
	global_load_lds_dwordx4 v[146:147], off
	v_lshl_add_u64 v[146:147], s[70:71], 0, v[138:139]
	s_add_i32 m0, s6, 0x2000
	s_nop 0
	global_load_lds_dwordx4 v[146:147], off
	v_lshl_add_u64 v[146:147], v[232:233], 0, s[30:31]
	s_mov_b32 m0, s76
	s_nop 0
	global_load_lds_dwordx4 v[146:147], off
	v_lshl_add_u64 v[146:147], v[234:235], 0, s[30:31]
	s_mov_b32 m0, s77
	s_nop 0
	global_load_lds_dwordx4 v[146:147], off
	s_and_b64 vcc, exec, s[18:19]
	s_cbranch_vccnz .Llw4_3a
	s_waitcnt vmcnt(8)
.Llw4_3a:
	s_waitcnt lgkmcnt(0)
	s_barrier
	s_waitcnt lgkmcnt(0)
	v_mfma_f32_16x16x32_bf16 v[64:67], v[152:155], v[200:203], v[64:67]
	v_mfma_f32_16x16x32_bf16 v[56:59], v[160:163], v[200:203], v[56:59]
	v_mfma_f32_16x16x32_bf16 v[48:51], v[152:155], v[208:211], v[48:51]
	v_mfma_f32_16x16x32_bf16 v[40:43], v[160:163], v[208:211], v[40:43]
	v_mfma_f32_16x16x32_bf16 v[32:35], v[152:155], v[216:219], v[32:35]
	v_mfma_f32_16x16x32_bf16 v[24:27], v[160:163], v[216:219], v[24:27]
	v_mfma_f32_16x16x32_bf16 v[16:19], v[152:155], v[224:227], v[16:19]
	v_mfma_f32_16x16x32_bf16 v[8:11], v[160:163], v[224:227], v[8:11]
	v_mfma_f32_16x16x32_bf16 v[64:67], v[156:159], v[204:207], v[64:67]
	v_mfma_f32_16x16x32_bf16 v[56:59], v[168:171], v[204:207], v[56:59]
	v_mfma_f32_16x16x32_bf16 v[48:51], v[156:159], v[212:215], v[48:51]
	v_mfma_f32_16x16x32_bf16 v[40:43], v[168:171], v[212:215], v[40:43]
	v_mfma_f32_16x16x32_bf16 v[32:35], v[156:159], v[220:223], v[32:35]
	v_mfma_f32_16x16x32_bf16 v[24:27], v[168:171], v[220:223], v[24:27]
	v_mfma_f32_16x16x32_bf16 v[16:19], v[156:159], v[228:231], v[16:19]
	v_mfma_f32_16x16x32_bf16 v[8:11], v[168:171], v[228:231], v[8:11]
	v_mfma_f32_16x16x32_bf16 v[60:63], v[174:177], v[200:203], v[60:63]
	v_mfma_f32_16x16x32_bf16 v[52:55], v[182:185], v[200:203], v[52:55]
	v_mfma_f32_16x16x32_bf16 v[44:47], v[174:177], v[208:211], v[44:47]
	v_mfma_f32_16x16x32_bf16 v[36:39], v[182:185], v[208:211], v[36:39]
	v_mfma_f32_16x16x32_bf16 v[28:31], v[174:177], v[216:219], v[28:31]
	v_mfma_f32_16x16x32_bf16 v[20:23], v[182:185], v[216:219], v[20:23]
	v_mfma_f32_16x16x32_bf16 v[12:15], v[174:177], v[224:227], v[12:15]
	v_mfma_f32_16x16x32_bf16 v[4:7], v[182:185], v[224:227], v[4:7]
	v_mfma_f32_16x16x32_bf16 v[60:63], v[178:181], v[204:207], v[60:63]
	v_mfma_f32_16x16x32_bf16 v[52:55], v[186:189], v[204:207], v[52:55]
	v_mfma_f32_16x16x32_bf16 v[44:47], v[178:181], v[212:215], v[44:47]
	v_mfma_f32_16x16x32_bf16 v[36:39], v[186:189], v[212:215], v[36:39]
	v_mfma_f32_16x16x32_bf16 v[28:31], v[178:181], v[220:223], v[28:31]
	v_mfma_f32_16x16x32_bf16 v[20:23], v[186:189], v[220:223], v[20:23]
	v_mfma_f32_16x16x32_bf16 v[12:15], v[178:181], v[228:231], v[12:15]
	v_mfma_f32_16x16x32_bf16 v[4:7], v[186:189], v[228:231], v[4:7]
	s_cbranch_vccz .Llw4_3b
	s_waitcnt vmcnt(8)
.Llw4_3b:
	s_barrier
	s_add_i32 s80, s80, 2
	s_add_u32 s68, s68, 0x100
	s_addc_u32 s69, s69, 0
	s_add_u32 s61, s61, 0x100
	s_addc_u32 s67, s67, 0
.LBB0_664:
	s_add_u32 s6, s68, 0xfffc0080
	s_addc_u32 s33, s69, -1
	s_add_i32 s82, 0, 0x10000
	s_cmp_eq_u32 s80, 12
	s_cselect_b32 s73, s10, s33
	s_cselect_b32 s72, s11, s6
	v_add_u32_e32 v2, s82, v148
	s_cselect_b32 s71, s15, s67
	s_cselect_b32 s70, s59, s61
	s_add_i32 s6, 0, 0x14000
	ds_read_b128 v[152:155], v2
	ds_read_b128 v[156:159], v2 offset:1024
	ds_read_b128 v[160:163], v2 offset:2048
	ds_read_b128 v[168:171], v2 offset:3072
	v_add_u32_e32 v2, s6, v148
	ds_read_b128 v[174:177], v2
	ds_read_b128 v[178:181], v2 offset:1024
	ds_read_b128 v[182:185], v2 offset:2048
	ds_read_b128 v[186:189], v2 offset:3072
	v_lshl_add_u64 v[146:147], s[68:69], 0, v[142:143]
	s_add_i32 m0, s35, 0xc000
	ds_read_b128 v[200:203], v151
	ds_read_b128 v[204:207], v151 offset:1024
	ds_read_b128 v[208:211], v151 offset:2048
	ds_read_b128 v[212:215], v151 offset:3072
	ds_read_b128 v[216:219], v151 offset:4096
	ds_read_b128 v[220:223], v151 offset:5120
	ds_read_b128 v[224:227], v151 offset:6144
	ds_read_b128 v[228:231], v151 offset:7168
	global_load_lds_dwordx4 v[146:147], off
	v_lshl_add_u64 v[146:147], s[68:69], 0, v[144:145]
	s_add_i32 m0, s35, 0xe000
	s_nop 0
	global_load_lds_dwordx4 v[146:147], off
	s_and_b64 vcc, exec, s[18:19]
	s_cbranch_vccnz .Llw4_4a
	s_waitcnt vmcnt(8)

.Llw4_7b:
	s_barrier
	s_add_i32 s80, s80, 2
	s_add_u32 s68, s68, 0x100
	s_addc_u32 s69, s69, 0
	s_add_u32 s61, s61, 0x100
	s_addc_u32 s67, s67, 0
	s_cmp_gt_u32 s80, 13
	s_cbranch_scc0 .LBB0_664
	s_and_b64 vcc, exec, s[18:19]
	s_cbranch_vccz .LBB0_667
	s_barrier
